# attention common path: threshold test on per-lane partial max (cross-half swap only on the rescale path), shorter max/sum chains
# speedup vs baseline: 1.0532x; 1.0030x over previous
.LBB0_2407:
	s_or_b64 exec, exec, s[26:27]
	global_load_dwordx4 v[96:99], v[106:107], off
	s_add_i32 s26, s13, -1
	s_and_b32 s28, s13, 1
	v_cmp_le_i32_e32 vcc, s26, v114
	s_and_saveexec_b64 s[26:27], vcc
	s_cbranch_execz .LBB0_2409
	s_mul_i32 s29, s28, 0x5800
	s_add_i32 s29, s29, 0
	v_add3_u32 v119, s29, v116, v192
	ds_read_b128 v[32:35], v119 offset:6656
	ds_read_b128 v[36:39], v119
	ds_read_b128 v[120:123], v119 offset:32
	ds_read_b128 v[124:127], v119 offset:6688
	s_waitcnt lgkmcnt(2)
	v_mfma_f32_32x32x16_bf16 v[48:63], v[36:39], v[88:91], v[136:151]
	v_mfma_f32_32x32x16_bf16 v[32:47], v[32:35], v[88:91], v[136:151]
	s_waitcnt lgkmcnt(1)
	v_mfma_f32_32x32x16_bf16 v[48:63], v[120:123], v[84:87], v[48:63]
	s_waitcnt lgkmcnt(0)
	v_mfma_f32_32x32x16_bf16 v[32:47], v[124:127], v[84:87], v[32:47]
	ds_read_b128 v[120:123], v119 offset:64
	ds_read_b128 v[124:127], v119 offset:6720
	s_waitcnt lgkmcnt(1)
	v_mfma_f32_32x32x16_bf16 v[48:63], v[120:123], v[80:83], v[48:63]
	s_waitcnt lgkmcnt(0)
	v_mfma_f32_32x32x16_bf16 v[32:47], v[124:127], v[80:83], v[32:47]
	ds_read_b128 v[120:123], v119 offset:96
	ds_read_b128 v[124:127], v119 offset:6752
	s_waitcnt lgkmcnt(1)
	v_mfma_f32_32x32x16_bf16 v[48:63], v[120:123], v[76:79], v[48:63]
	s_waitcnt lgkmcnt(0)
	v_mfma_f32_32x32x16_bf16 v[32:47], v[124:127], v[76:79], v[32:47]
	ds_read_b128 v[120:123], v119 offset:128
	ds_read_b128 v[124:127], v119 offset:6784
	s_waitcnt lgkmcnt(1)
	v_mfma_f32_32x32x16_bf16 v[48:63], v[120:123], v[72:75], v[48:63]
	s_waitcnt lgkmcnt(0)
	v_mfma_f32_32x32x16_bf16 v[32:47], v[124:127], v[72:75], v[32:47]
	ds_read_b128 v[120:123], v119 offset:160
	ds_read_b128 v[124:127], v119 offset:6816
	s_waitcnt lgkmcnt(1)
	v_mfma_f32_32x32x16_bf16 v[48:63], v[120:123], v[68:71], v[48:63]
	s_waitcnt lgkmcnt(0)
	v_mfma_f32_32x32x16_bf16 v[32:47], v[124:127], v[68:71], v[32:47]
	v_add3_u32 v168, s29, v117, v192
	ds_read_b128 v[152:155], v168 offset:13312
	ds_read_b128 v[156:159], v168 offset:17920
	ds_read_b128 v[160:163], v168 offset:13344
	ds_read_b128 v[164:167], v168 offset:17952
	ds_read_b128 v[128:131], v168 offset:13376
	ds_read_b128 v[132:135], v168 offset:17984
	ds_read_b128 v[172:175], v168 offset:13408
	ds_read_b128 v[176:179], v168 offset:18016
	s_nop 1
	v_max_f32_e32 v119, v48, v49
	v_max3_f32 v119, v119, v50, v51
	v_max3_f32 v119, v119, v52, v53
	v_max3_f32 v119, v119, v54, v55
	v_max3_f32 v119, v119, v56, v57
	v_max3_f32 v119, v119, v58, v59
	v_max3_f32 v119, v119, v60, v61
	v_max3_f32 v119, v119, v62, v63
	v_max3_f32 v119, v119, v32, v33
	v_max3_f32 v119, v119, v34, v35
	v_max3_f32 v119, v119, v36, v37
	v_max3_f32 v119, v119, v38, v39
	v_max3_f32 v119, v119, v40, v41
	v_max3_f32 v119, v119, v42, v43
	v_max3_f32 v119, v119, v44, v45
	v_max3_f32 v119, v119, v46, v47
	v_cmp_lt_f32_e32 vcc, 0x41000000, v119
	s_cbranch_vccnz .Lattn_rare
.Lattn_common:
	v_exp_f32_e32 v48, v48
	v_exp_f32_e32 v49, v49
	v_exp_f32_e32 v50, v50
	v_exp_f32_e32 v51, v51
	v_add_f32_e32 v169, v48, v49
	v_exp_f32_e32 v52, v52
	v_add_f32_e32 v169, v50, v169
	v_exp_f32_e32 v53, v53
	v_add_f32_e32 v169, v51, v169
	v_exp_f32_e32 v54, v54
	v_add_f32_e32 v169, v52, v169
	v_exp_f32_e32 v55, v55
	v_add_f32_e32 v169, v53, v169
	v_add_f32_e32 v169, v54, v169
	v_cvt_pk_bf16_f32 v180, v48, v49
	v_add_f32_e32 v169, v55, v169
	v_cvt_pk_bf16_f32 v181, v50, v51
	v_cvt_pk_bf16_f32 v182, v52, v53
	v_cvt_pk_bf16_f32 v183, v54, v55
	v_exp_f32_e32 v56, v56
	v_exp_f32_e32 v57, v57
	s_waitcnt lgkmcnt(6)
	v_mfma_f32_32x32x16_bf16 v[16:31], v[152:155], v[180:183], v[16:31]
	v_mfma_f32_32x32x16_bf16 v[0:15], v[156:159], v[180:183], v[0:15]
	v_exp_f32_e32 v58, v58
	v_add_f32_e32 v169, v56, v169
	v_exp_f32_e32 v59, v59
	v_add_f32_e32 v169, v57, v169
	v_exp_f32_e32 v60, v60
	v_add_f32_e32 v169, v58, v169
	v_exp_f32_e32 v61, v61
	v_add_f32_e32 v169, v59, v169
	v_exp_f32_e32 v62, v62
	v_add_f32_e32 v169, v60, v169
	v_exp_f32_e32 v63, v63
	v_add_f32_e32 v169, v61, v169
	v_add_f32_e32 v169, v62, v169
	v_cvt_pk_bf16_f32 v184, v56, v57
	v_add_f32_e32 v169, v63, v169
	v_cvt_pk_bf16_f32 v185, v58, v59
	v_cvt_pk_bf16_f32 v186, v60, v61
	v_cvt_pk_bf16_f32 v187, v62, v63
	v_exp_f32_e32 v32, v32
	v_exp_f32_e32 v33, v33
	s_waitcnt lgkmcnt(4)
	v_mfma_f32_32x32x16_bf16 v[16:31], v[160:163], v[184:187], v[16:31]
	v_mfma_f32_32x32x16_bf16 v[0:15], v[164:167], v[184:187], v[0:15]
	v_exp_f32_e32 v34, v34
	v_add_f32_e32 v169, v32, v169
	v_exp_f32_e32 v35, v35
	v_add_f32_e32 v169, v33, v169
	v_exp_f32_e32 v36, v36
	v_add_f32_e32 v169, v34, v169
	v_exp_f32_e32 v37, v37
	v_add_f32_e32 v169, v35, v169
	v_exp_f32_e32 v38, v38
	v_add_f32_e32 v169, v36, v169
	v_exp_f32_e32 v39, v39
	v_add_f32_e32 v169, v37, v169
	v_add_f32_e32 v169, v38, v169
	v_cvt_pk_bf16_f32 v180, v32, v33
	v_add_f32_e32 v169, v39, v169
	v_cvt_pk_bf16_f32 v181, v34, v35
	v_cvt_pk_bf16_f32 v182, v36, v37
	v_cvt_pk_bf16_f32 v183, v38, v39
	v_exp_f32_e32 v40, v40
	v_exp_f32_e32 v41, v41
	s_waitcnt lgkmcnt(2)
	v_mfma_f32_32x32x16_bf16 v[16:31], v[128:131], v[180:183], v[16:31]
	v_mfma_f32_32x32x16_bf16 v[0:15], v[132:135], v[180:183], v[0:15]
	v_exp_f32_e32 v42, v42
	v_add_f32_e32 v169, v40, v169
	v_exp_f32_e32 v43, v43
	v_add_f32_e32 v169, v41, v169
	v_exp_f32_e32 v44, v44
	v_add_f32_e32 v169, v42, v169
	v_exp_f32_e32 v45, v45
	v_add_f32_e32 v169, v43, v169
	v_exp_f32_e32 v46, v46
	v_add_f32_e32 v169, v44, v169
	v_exp_f32_e32 v47, v47
	v_add_f32_e32 v169, v45, v169
	v_add_f32_e32 v169, v46, v169
	v_cvt_pk_bf16_f32 v184, v40, v41
	v_add_f32_e32 v169, v47, v169
	v_cvt_pk_bf16_f32 v185, v42, v43
	v_cvt_pk_bf16_f32 v186, v44, v45
	v_cvt_pk_bf16_f32 v187, v46, v47
	v_add_f32_e32 v115, v115, v169
	s_nop 0
	s_waitcnt lgkmcnt(0)
	v_mfma_f32_32x32x16_bf16 v[16:31], v[172:175], v[184:187], v[16:31]
	v_mfma_f32_32x32x16_bf16 v[0:15], v[176:179], v[184:187], v[0:15]
	s_branch .Lattn_blk_end
.Lattn_rare:
	v_mov_b32_e32 v120, v119
	s_nop 1
	v_permlane32_swap_b32_e32 v119, v120
	v_max_f32_e32 v119, v119, v120
	v_max_f32_e32 v170, 0, v119
	v_exp_f32_e64 v171, -v170
	v_add_f32_e32 v118, v118, v170
	v_sub_f32_e32 v48, v48, v170
	v_sub_f32_e32 v49, v49, v170
	v_sub_f32_e32 v50, v50, v170
	v_sub_f32_e32 v51, v51, v170
	v_sub_f32_e32 v52, v52, v170
	v_sub_f32_e32 v53, v53, v170
	v_sub_f32_e32 v54, v54, v170
	v_sub_f32_e32 v55, v55, v170
	v_sub_f32_e32 v56, v56, v170
	v_sub_f32_e32 v57, v57, v170
	v_sub_f32_e32 v58, v58, v170
	v_sub_f32_e32 v59, v59, v170
	v_sub_f32_e32 v60, v60, v170
	v_sub_f32_e32 v61, v61, v170
	v_sub_f32_e32 v62, v62, v170
	v_sub_f32_e32 v63, v63, v170
	v_sub_f32_e32 v32, v32, v170
	v_sub_f32_e32 v33, v33, v170
	v_sub_f32_e32 v34, v34, v170
	v_sub_f32_e32 v35, v35, v170
	v_sub_f32_e32 v36, v36, v170
	v_sub_f32_e32 v37, v37, v170
	v_sub_f32_e32 v38, v38, v170
	v_sub_f32_e32 v39, v39, v170
	v_sub_f32_e32 v40, v40, v170
	v_sub_f32_e32 v41, v41, v170
	v_sub_f32_e32 v42, v42, v170
	v_sub_f32_e32 v43, v43, v170
	v_sub_f32_e32 v44, v44, v170
	v_sub_f32_e32 v45, v45, v170
	v_sub_f32_e32 v46, v46, v170
	v_sub_f32_e32 v47, v47, v170
	v_sub_f32_e32 v136, 0, v118
	v_sub_f32_e32 v137, 0, v118
	v_sub_f32_e32 v138, 0, v118
	v_sub_f32_e32 v139, 0, v118
	v_sub_f32_e32 v140, 0, v118
	v_sub_f32_e32 v141, 0, v118
	v_sub_f32_e32 v142, 0, v118
	v_sub_f32_e32 v143, 0, v118
	v_sub_f32_e32 v144, 0, v118
	v_sub_f32_e32 v145, 0, v118
	v_sub_f32_e32 v146, 0, v118
	v_sub_f32_e32 v147, 0, v118
	v_sub_f32_e32 v148, 0, v118
	v_sub_f32_e32 v149, 0, v118
	v_sub_f32_e32 v150, 0, v118
	v_sub_f32_e32 v151, 0, v118
	v_mul_f32_e32 v0, v171, v0
	v_mul_f32_e32 v1, v171, v1
	v_mul_f32_e32 v2, v171, v2
	v_mul_f32_e32 v3, v171, v3
	v_mul_f32_e32 v4, v171, v4
	v_mul_f32_e32 v5, v171, v5
	v_mul_f32_e32 v6, v171, v6
	v_mul_f32_e32 v7, v171, v7
	v_mul_f32_e32 v8, v171, v8
	v_mul_f32_e32 v9, v171, v9
	v_mul_f32_e32 v10, v171, v10
	v_mul_f32_e32 v11, v171, v11
	v_mul_f32_e32 v12, v171, v12
	v_mul_f32_e32 v13, v171, v13
	v_mul_f32_e32 v14, v171, v14
	v_mul_f32_e32 v15, v171, v15
	v_mul_f32_e32 v16, v171, v16
	v_mul_f32_e32 v17, v171, v17
	v_mul_f32_e32 v18, v171, v18
	v_mul_f32_e32 v19, v171, v19
	v_mul_f32_e32 v20, v171, v20
	v_mul_f32_e32 v21, v171, v21
	v_mul_f32_e32 v22, v171, v22
	v_mul_f32_e32 v23, v171, v23
	v_mul_f32_e32 v24, v171, v24
	v_mul_f32_e32 v25, v171, v25
	v_mul_f32_e32 v26, v171, v26
	v_mul_f32_e32 v27, v171, v27
	v_mul_f32_e32 v28, v171, v28
	v_mul_f32_e32 v29, v171, v29
	v_mul_f32_e32 v30, v171, v30
	v_mul_f32_e32 v31, v171, v31
	v_mul_f32_e32 v115, v171, v115
	s_branch .Lattn_common
